# S5 sample tasks moved to workgroups 128..255 (attention sample tasks stay on 0..127)
# speedup vs baseline: 1.1833x; 1.0131x over previous
; DI void mixers_phase(ArgsP a, LAS unsigned char* lds, int l, int tid) {
;     ...
;     const int wave = tid >> 6, lane = tid & 63, gw = blockIdx.x * 8 + wave, NGW = gridDim.x * 8;
;     const int vcb = (gridDim.x % 8 == 0) ? (blockIdx.x % 8) * (gridDim.x / 8) + blockIdx.x / 8 : blockIdx.x;
;     for (int rp = 0; rp < 1 + ((MIXM >> 0) & 1); ++rp) for (int u = vcb; u < 256; u += gridDim.x) attn_prompt_unit(lds, u, Q, KB, VB, YB, a->in[16] + l * 8, tid);
;     for (int rp = 0; rp < 1 + ((MIXM >> 1) & 1); ++rp) for (int t = vcb; t < 256; t += gridDim.x) s5_prompt_task(lds, t, l, a, U, YC0, tid);
;     for (int rp = 0; rp < 1 + ((MIXM >> 2) & 1); ++rp) for (int t = gw; t < 4096; t += NGW) s5_sample_task(lds, t, l, a, U, YC0, tid);
;     __syncthreads();
;     for (int rp = 0; rp < 1 + ((MIXM >> 3) & 1); ++rp) for (int t = gw; t < 1024; t += NGW) attn_sample_task(lds + wave * 4096, t, l, a, Q, YB, lane);
.LBB0_954:
	v_add_u32_e32 v100, s83, v157
	v_mov_b32_e32 v101, v100
	v_mov_b32_e32 v234, s48
	s_cmpk_lg_i32 s82, 0x100
	s_cbranch_scc1 .Ls5s_orig
	v_add_u32_e32 v101, 0xfffffc00, v100
	v_mov_b32_e32 v234, 0x400
.Ls5s_orig:
	s_movk_i32 s8, 0x1000
	v_cmp_gt_u32_e32 vcc, s8, v101
	s_and_saveexec_b64 s[30:31], vcc
	s_cbranch_execz .LBB0_965
	s_load_dwordx2 s[40:41], s[34:35], 0xc0
	s_load_dwordx4 s[12:15], s[34:35], 0x28
	s_lshl_b64 s[28:29], s[28:29], 2
	v_mov_b32_e32 v137, v97
	v_cmp_gt_u32_e64 s[8:9], 4, v132
	s_waitcnt lgkmcnt(0)
	s_add_u32 s28, s40, s28
	s_addc_u32 s29, s41, s29
	v_cmp_gt_u32_e64 s[10:11], 4, v131
	v_lshl_add_u64 v[84:85], s[28:29], 0, v[136:137]
	s_mov_b64 s[28:29], 0
	s_branch .LBB0_957
.LBB0_956:
	s_or_b64 exec, exec, s[40:41]
	v_add_u32_e32 v101, v234, v101
	s_movk_i32 s39, 0xfff
	v_cmp_lt_i32_e32 vcc, s39, v101
	s_or_b64 s[28:29], vcc, s[28:29]
	s_andn2_b64 exec, exec, s[28:29]
	s_cbranch_execz .LBB0_965
